# attention phase: static priority raise for waves 0-3 (one wave per SIMD) for the whole phase
# speedup vs baseline: 1.0070x; 1.0003x over previous
; #define LAS __attribute__((address_space(3)))
; __device__ __forceinline__ void attn_block(KP p, LAS unsigned char* lds, int bh, int q0) {
;     int tid = threadIdx.x; asm volatile("" : "+v"(tid));
;     const int lane = tid & 63, w = __builtin_amdgcn_readfirstlane(tid >> 6), lr = lane & 31, lh = lane >> 5;
;     unsigned char* ws = p->ws;
;     const bf16_t* Qg = (const bf16_t*)(ws + OFF_Q) + (size_t)bh * SEQ * 96;
;     const bf16_t* Kg = (const bf16_t*)(ws + OFF_K) + (size_t)bh * SEQ * 96;
;     const bf16_t* Vg = (const bf16_t*)(ws + OFF_VT) + (size_t)bh * 64 * SEQ;
;     const int qrow = q0 + 32 * w + lr, wave_q0 = q0 + 32 * w;
; __global__ void __launch_bounds__(512) fwd_kernel(Params p_arg) {
;     ...
;             for (int it0 = blockIdx.x; it0 < 256; it0 += gridDim.x) { const int it = (it0 & 7) * 32 + (it0 >> 3);
;                 const int bh = it >> 3, pr = it & 7; attn_block(p, lds, bh, 256 * pr); attn_block(p, lds, bh, 256 * (15 - pr)); }
.LBB0_235:
	s_andn2_b64 vcc, exec, s[4:5]
	s_cbranch_vccnz .LBB0_468
	s_cmp_lt_i32 s88, 1
	s_mov_b64 s[4:5], -1
	s_cbranch_scc1 .LBB0_436
	v_readlane_b32 s6, v253, 62
	v_readlane_b32 s7, v253, 63
	s_cmp_gt_i32 s88, 1
	s_nop 0
	v_cndmask_b32_e64 v0, 0, 1, s[6:7]
	v_cmp_ne_u32_e64 s[40:41], 1, v0
	s_cbranch_scc0 .LBB0_278
	s_and_b64 vcc, exec, s[40:41]
	s_movk_i32 s58, 0xd0
	s_mov_b32 s86, 0x110b0000
	s_cbranch_vccnz .LBB0_277
	s_waitcnt lgkmcnt(0)
	v_readfirstlane_b32 s6, v167
	s_nop 3
	s_cmp_ge_u32 s6, 0x100
	s_cbranch_scc1 .Lattn_prio_done
	s_setprio 1
.Lattn_prio_done:
	s_branch .Lpad_ap
	s_nop 0
	s_nop 0
	s_nop 0
	s_nop 0
	s_nop 0
	s_nop 0
	s_nop 0
	s_nop 0
	s_nop 0
.Lpad_ap:
	s_add_u32 s44, s94, 0x150b0000
	s_addc_u32 s45, s95, 0
	s_add_u32 s46, s94, 0x168b0000
	s_addc_u32 s47, s95, 0
	s_add_u32 s48, s94, 0x180b0000
	s_addc_u32 s49, s95, 0
	s_add_u32 s4, s94, 0x9c30000
	s_addc_u32 s5, s95, 0
	s_mov_b32 s54, s2
	s_branch .LBB0_241

; __global__ void __launch_bounds__(512) fwd_kernel(Params p_arg) {
;     ...
;                 const int bh = it >> 3, pr = it & 7; attn_block(p, lds, bh, 256 * pr); attn_block(p, lds, bh, 256 * (15 - pr)); }
.LBB0_277:
	s_setprio 0
	s_branch .Lpad_ap2
	s_nop 0
	s_nop 0
	s_nop 0
	s_nop 0
	s_nop 0
	s_nop 0
	s_nop 0
	s_nop 0
	s_nop 0
	s_nop 0
	s_nop 0
	s_nop 0
	s_nop 0
	s_nop 0
